# plus: diff map-1 epilogue issues the eight per-row gate loads together ahead of the row loop (was one dependent load per row)
# baseline (speedup 1.0000x reference)
; #define LAS __attribute__((address_space(3)))
; __device__ __forceinline__ unsigned f2bf(float f) { unsigned u = __builtin_bit_cast(unsigned, f); return (u + 0x7fffu + ((u >> 16) & 1u)) >> 16; }
; __device__ __forceinline__ int crow(int r, int hi) { return (r & 3) + 8 * (r >> 2) + 4 * hi; }
; template <bool NOMAX>
; __device__ __forceinline__ void diff_unit(const AttnCtx& C, int u, LAS unsigned char* lds) {
;     ...
;         if (tidf == 0) { unsigned sp = 0; while (__hip_atomic_load(C.flags + 16 * (qb * 4 + h), __ATOMIC_RELAXED, __HIP_MEMORY_SCOPE_AGENT) == 0u) { __builtin_amdgcn_s_sleep(8); if (++sp > (1u << 22)) break; }
;             __builtin_amdgcn_fence(__ATOMIC_ACQUIRE, "agent"); asm volatile("s_waitcnt vmcnt(0)" ::: "memory"); }
;         __syncthreads();
;         const f32x4* st = (const f32x4*)(C.stash + (slot * 512 + tidf) * 64);
;         LAS bf16* stg = (LAS bf16*)(lds + TD_OST) + wid * (32 * 128);
; #pragma unroll
;         for (int d = 0; d < 4; ++d)
; #pragma unroll
;             for (int gq = 0; gq < 4; ++gq) { const f32x4 s1 = st[d * 4 + gq];
; #pragma unroll
;                 for (int e = 0; e < 4; ++e) { const int r = 4 * gq + e; stg[crow(r, hi) * 128 + 32 * d + r32] = (bf16)f2bf(s1[e] - C.lam * (o[d][r] * rli[r])); } }
.LBB0_532:
	s_or_b64 exec, exec, s[6:7]
	v_ashrrev_i32_e32 v9, 31, v8
	v_lshlrev_b64 v[4:5], 17, v[2:3]
	v_lshl_add_u64 v[4:5], s[12:13], 0, v[4:5]
	v_lshlrev_b64 v[6:7], 8, v[8:9]
	v_lshl_add_u64 v[92:93], v[4:5], 0, v[6:7]
	s_barrier
	global_load_dwordx4 v[96:99], v[92:93], off
	global_load_dwordx4 v[100:103], v[92:93], off offset:16
	global_load_dwordx4 v[104:107], v[92:93], off offset:32
	global_load_dwordx4 v[108:111], v[92:93], off offset:48
	global_load_dwordx4 v[4:7], v[92:93], off offset:80
	global_load_dwordx4 v[112:115], v[92:93], off offset:64
	global_load_dwordx4 v[116:119], v[92:93], off offset:112
	global_load_dwordx4 v[120:123], v[92:93], off offset:96
	v_mul_f32_e32 v95, v68, v90
	s_lshl_b32 s0, s0, 1
	v_mul_f32_e32 v124, v69, v91
	v_mul_f32_e32 v125, v70, v88
	v_mul_f32_e32 v126, v71, v89
	v_mul_f32_e32 v127, v72, v14
	v_mul_f32_e32 v128, v73, v15
	v_mul_f32_e32 v129, v74, v86
	v_mul_f32_e32 v130, v75, v87
	v_mul_f32_e32 v131, v76, v84
	v_mul_f32_e32 v132, v77, v85
	v_mul_f32_e32 v133, v78, v16
	v_mul_f32_e32 v134, v79, v17
	v_mul_f32_e32 v135, v80, v12
	v_mul_f32_e32 v136, v81, v13
	v_lshlrev_b32_e32 v9, 1, v210
	s_add_i32 s0, s0, 0
	v_add3_u32 v9, s0, v9, v201
	v_readlane_b32 s8, v253, 60
	v_readlane_b32 s9, v253, 61
	v_mov_b32_e32 v219, v3
	v_readlane_b32 s60, v253, 32
	v_readlane_b32 s72, v253, 44
	v_readlane_b32 s73, v253, 45
	v_readlane_b32 s6, v253, 28
	v_readlane_b32 s7, v253, 29
	v_readlane_b32 s61, v253, 33
	v_readlane_b32 s62, v253, 34
	v_readlane_b32 s63, v253, 35
	v_readlane_b32 s64, v253, 36
	v_readlane_b32 s65, v253, 37
	v_readlane_b32 s66, v253, 38
	v_readlane_b32 s67, v253, 39
	v_readlane_b32 s68, v253, 40
	v_readlane_b32 s69, v253, 41
	v_readlane_b32 s70, v253, 42
	v_readlane_b32 s71, v253, 43
	v_readlane_b32 s74, v253, 46
	v_readlane_b32 s75, v253, 47
	s_waitcnt vmcnt(7)
	v_fma_f32 v95, -v216, v95, v96
	v_fma_f32 v96, -v216, v124, v97
	v_fma_f32 v97, -v216, v125, v98
	v_fma_f32 v98, -v216, v126, v99
	s_waitcnt vmcnt(6)
	v_fma_f32 v99, -v216, v127, v100
	v_fma_f32 v100, -v216, v128, v101
	v_fma_f32 v101, -v216, v129, v102
	v_fma_f32 v102, -v216, v130, v103
	s_waitcnt vmcnt(5)
	v_fma_f32 v103, -v216, v131, v104
	v_fma_f32 v104, -v216, v132, v105
	v_fma_f32 v105, -v216, v133, v106
	v_fma_f32 v106, -v216, v134, v107
	s_waitcnt vmcnt(4)
	v_fma_f32 v107, -v216, v135, v108
	v_fma_f32 v108, -v216, v136, v109
	v_bfe_u32 v109, v95, 16, 1
	v_bfe_u32 v124, v96, 16, 1
	v_bfe_u32 v125, v97, 16, 1
	v_bfe_u32 v126, v98, 16, 1
	v_bfe_u32 v127, v99, 16, 1
	v_bfe_u32 v128, v100, 16, 1
	v_bfe_u32 v129, v101, 16, 1
	v_bfe_u32 v130, v102, 16, 1
	v_bfe_u32 v131, v103, 16, 1
	v_bfe_u32 v132, v104, 16, 1
	v_bfe_u32 v133, v105, 16, 1
	v_bfe_u32 v134, v106, 16, 1
	v_bfe_u32 v135, v107, 16, 1
	v_add3_u32 v95, v95, v109, s55
	v_add3_u32 v96, v96, v124, s55
	v_add3_u32 v97, v97, v125, s55
	v_add3_u32 v98, v98, v126, s55
	v_add3_u32 v99, v99, v127, s55
	v_add3_u32 v100, v100, v128, s55
	v_add3_u32 v101, v101, v129, s55
	v_add3_u32 v102, v102, v130, s55
	v_add3_u32 v103, v103, v131, s55
	v_add3_u32 v104, v104, v132, s55
	v_add3_u32 v105, v105, v133, s55
	v_add3_u32 v106, v106, v134, s55
	v_add3_u32 v107, v107, v135, s55
	ds_write_b16_d16_hi v9, v95
	ds_write_b16_d16_hi v9, v96 offset:256
	ds_write_b16_d16_hi v9, v97 offset:512
	ds_write_b16_d16_hi v9, v98 offset:768
	ds_write_b16_d16_hi v9, v99 offset:2048
	ds_write_b16_d16_hi v9, v100 offset:2304
	ds_write_b16_d16_hi v9, v101 offset:2560
	ds_write_b16_d16_hi v9, v102 offset:2816
	ds_write_b16_d16_hi v9, v103 offset:4096
	ds_write_b16_d16_hi v9, v104 offset:4352
	ds_write_b16_d16_hi v9, v105 offset:4608
	ds_write_b16_d16_hi v9, v106 offset:4864
	ds_write_b16_d16_hi v9, v107 offset:6144
	v_bfe_u32 v95, v108, 16, 1
	v_add3_u32 v95, v108, v95, s55
	ds_write_b16_d16_hi v9, v95 offset:6400
	v_mul_f32_e32 v95, v82, v10
	v_fma_f32 v95, -v216, v95, v110
	v_bfe_u32 v96, v95, 16, 1
	v_add3_u32 v95, v95, v96, s55
	ds_write_b16_d16_hi v9, v95 offset:6656
	v_mul_f32_e32 v95, v83, v11
	v_fma_f32 v95, -v216, v95, v111
	v_bfe_u32 v96, v95, 16, 1
	v_add3_u32 v95, v95, v96, s55
	ds_write_b16_d16_hi v9, v95 offset:6912
	v_mul_f32_e32 v95, v52, v90
	s_waitcnt vmcnt(2)
	v_fma_f32 v95, -v216, v95, v112
	v_bfe_u32 v96, v95, 16, 1
	v_add3_u32 v95, v95, v96, s55
	global_load_dwordx4 v[96:99], v[92:93], off offset:144
	global_load_dwordx4 v[100:103], v[92:93], off offset:128
	ds_write_b16_d16_hi v9, v95 offset:64
	v_mul_f32_e32 v95, v53, v91
	v_fma_f32 v95, -v216, v95, v113
	v_bfe_u32 v104, v95, 16, 1
	v_add3_u32 v95, v95, v104, s55
	ds_write_b16_d16_hi v9, v95 offset:320
	v_mul_f32_e32 v95, v54, v88
	v_fma_f32 v95, -v216, v95, v114
	v_bfe_u32 v104, v95, 16, 1
	v_add3_u32 v95, v95, v104, s55
	ds_write_b16_d16_hi v9, v95 offset:576
	v_mul_f32_e32 v95, v55, v89
	v_fma_f32 v95, -v216, v95, v115
	v_bfe_u32 v104, v95, 16, 1
	v_add3_u32 v95, v95, v104, s55
	ds_write_b16_d16_hi v9, v95 offset:832
	v_mul_f32_e32 v95, v56, v14
	v_fma_f32 v4, -v216, v95, v4
	v_bfe_u32 v95, v4, 16, 1
	v_add3_u32 v4, v4, v95, s55
	ds_write_b16_d16_hi v9, v4 offset:2112
	v_mul_f32_e32 v4, v57, v15
	v_fma_f32 v4, -v216, v4, v5
	v_bfe_u32 v5, v4, 16, 1
	v_add3_u32 v4, v4, v5, s55
	ds_write_b16_d16_hi v9, v4 offset:2368
	v_mul_f32_e32 v4, v58, v86
	v_fma_f32 v4, -v216, v4, v6
	v_bfe_u32 v5, v4, 16, 1
	v_add3_u32 v4, v4, v5, s55
	ds_write_b16_d16_hi v9, v4 offset:2624
	v_mul_f32_e32 v4, v59, v87
	v_fma_f32 v4, -v216, v4, v7
	v_bfe_u32 v5, v4, 16, 1
	v_add3_u32 v4, v4, v5, s55
	ds_write_b16_d16_hi v9, v4 offset:2880
	v_mul_f32_e32 v4, v60, v84
	s_waitcnt vmcnt(2)
; #define LAS __attribute__((address_space(3)))
; __device__ __forceinline__ unsigned f2bf(float f) { unsigned u = __builtin_bit_cast(unsigned, f); return (u + 0x7fffu + ((u >> 16) & 1u)) >> 16; }
; __device__ __forceinline__ int crow(int r, int hi) { return (r & 3) + 8 * (r >> 2) + 4 * hi; }
; template <bool NOMAX>
; __device__ __forceinline__ void diff_unit(const AttnCtx& C, int u, LAS unsigned char* lds) {
;     ...
;         if (tidf == 0) { unsigned sp = 0; while (__hip_atomic_load(C.flags + 16 * (qb * 4 + h), __ATOMIC_RELAXED, __HIP_MEMORY_SCOPE_AGENT) == 0u) { __builtin_amdgcn_s_sleep(8); if (++sp > (1u << 22)) break; }
;             __builtin_amdgcn_fence(__ATOMIC_ACQUIRE, "agent"); asm volatile("s_waitcnt vmcnt(0)" ::: "memory"); }
;         __syncthreads();
;         const f32x4* st = (const f32x4*)(C.stash + (slot * 512 + tidf) * 64);
;         LAS bf16* stg = (LAS bf16*)(lds + TD_OST) + wid * (32 * 128);
; #pragma unroll
;         for (int d = 0; d < 4; ++d)
; #pragma unroll
;             for (int gq = 0; gq < 4; ++gq) { const f32x4 s1 = st[d * 4 + gq];
; #pragma unroll
;                 for (int e = 0; e < 4; ++e) { const int r = 4 * gq + e; stg[crow(r, hi) * 128 + 32 * d + r32] = (bf16)f2bf(s1[e] - C.lam * (o[d][r] * rli[r])); } }
	v_fma_f32 v4, -v216, v4, v120
	v_bfe_u32 v5, v4, 16, 1
	v_add3_u32 v95, v4, v5, s55
	global_load_dwordx4 v[4:7], v[92:93], off offset:176
	global_load_dwordx4 v[104:107], v[92:93], off offset:160
	ds_write_b16_d16_hi v9, v95 offset:4160
	v_mul_f32_e32 v95, v61, v85
	v_fma_f32 v95, -v216, v95, v121
	v_bfe_u32 v108, v95, 16, 1
	v_add3_u32 v95, v95, v108, s55
	ds_write_b16_d16_hi v9, v95 offset:4416
	v_mul_f32_e32 v95, v62, v16
	v_fma_f32 v95, -v216, v95, v122
	v_bfe_u32 v108, v95, 16, 1
	v_add3_u32 v95, v95, v108, s55
	ds_write_b16_d16_hi v9, v95 offset:4672
	v_mul_f32_e32 v95, v63, v17
	v_fma_f32 v95, -v216, v95, v123
	v_bfe_u32 v108, v95, 16, 1
	v_add3_u32 v95, v95, v108, s55
	ds_write_b16_d16_hi v9, v95 offset:4928
	v_mul_f32_e32 v95, v64, v12
	v_fma_f32 v95, -v216, v95, v116
	v_bfe_u32 v108, v95, 16, 1
	v_add3_u32 v95, v95, v108, s55
	ds_write_b16_d16_hi v9, v95 offset:6208
	v_mul_f32_e32 v95, v65, v13
	v_fma_f32 v95, -v216, v95, v117
	v_bfe_u32 v108, v95, 16, 1
	v_add3_u32 v95, v95, v108, s55
	ds_write_b16_d16_hi v9, v95 offset:6464
	v_mul_f32_e32 v95, v66, v10
	v_fma_f32 v95, -v216, v95, v118
	v_bfe_u32 v108, v95, 16, 1
	v_add3_u32 v95, v95, v108, s55
	ds_write_b16_d16_hi v9, v95 offset:6720
	v_mul_f32_e32 v95, v67, v11
	v_fma_f32 v95, -v216, v95, v119
	v_bfe_u32 v108, v95, 16, 1
	v_add3_u32 v95, v95, v108, s55
	ds_write_b16_d16_hi v9, v95 offset:6976
	v_mul_f32_e32 v95, v36, v90
	global_load_dwordx4 v[108:111], v[92:93], off offset:208
	global_load_dwordx4 v[112:115], v[92:93], off offset:192
	s_waitcnt vmcnt(4)
	v_fma_f32 v95, -v216, v95, v100
	v_bfe_u32 v100, v95, 16, 1
	v_add3_u32 v95, v95, v100, s55
	ds_write_b16_d16_hi v9, v95 offset:128
	v_mul_f32_e32 v95, v37, v91
	v_fma_f32 v95, -v216, v95, v101
	v_bfe_u32 v100, v95, 16, 1
	v_add3_u32 v95, v95, v100, s55
	ds_write_b16_d16_hi v9, v95 offset:384
	v_mul_f32_e32 v95, v38, v88
	v_fma_f32 v95, -v216, v95, v102
	v_bfe_u32 v100, v95, 16, 1
	v_add3_u32 v95, v95, v100, s55
	ds_write_b16_d16_hi v9, v95 offset:640
	v_mul_f32_e32 v95, v39, v89
	v_fma_f32 v95, -v216, v95, v103
	v_bfe_u32 v100, v95, 16, 1
	v_add3_u32 v95, v95, v100, s55
	ds_write_b16_d16_hi v9, v95 offset:896
	v_mul_f32_e32 v95, v40, v14
	v_fma_f32 v95, -v216, v95, v96
	v_bfe_u32 v96, v95, 16, 1
	v_add3_u32 v95, v95, v96, s55
	ds_write_b16_d16_hi v9, v95 offset:2176
	v_mul_f32_e32 v95, v41, v15
	v_fma_f32 v95, -v216, v95, v97
	v_bfe_u32 v96, v95, 16, 1
	v_add3_u32 v95, v95, v96, s55
	ds_write_b16_d16_hi v9, v95 offset:2432
	v_mul_f32_e32 v95, v42, v86
	v_fma_f32 v95, -v216, v95, v98
	v_bfe_u32 v96, v95, 16, 1
	v_add3_u32 v95, v95, v96, s55
	ds_write_b16_d16_hi v9, v95 offset:2688
	v_mul_f32_e32 v95, v43, v87
	v_fma_f32 v95, -v216, v95, v99
	v_bfe_u32 v96, v95, 16, 1
	v_add3_u32 v95, v95, v96, s55
	ds_write_b16_d16_hi v9, v95 offset:2944
	global_load_dwordx4 v[96:99], v[92:93], off offset:240
	global_load_dwordx4 v[100:103], v[92:93], off offset:224
	v_mul_f32_e32 v95, v44, v84
	s_waitcnt vmcnt(4)
	v_fma_f32 v95, -v216, v95, v104
	v_bfe_u32 v92, v95, 16, 1
	v_add3_u32 v92, v95, v92, s55
	ds_write_b16_d16_hi v9, v92 offset:4224
	v_mul_f32_e32 v92, v45, v85
	v_fma_f32 v92, -v216, v92, v105
	v_bfe_u32 v93, v92, 16, 1
	v_add3_u32 v92, v92, v93, s55
	ds_write_b16_d16_hi v9, v92 offset:4480
	v_mul_f32_e32 v92, v46, v16
	v_fma_f32 v92, -v216, v92, v106
	v_bfe_u32 v93, v92, 16, 1
	v_add3_u32 v92, v92, v93, s55
	ds_write_b16_d16_hi v9, v92 offset:4736
	v_mul_f32_e32 v92, v47, v17
	v_fma_f32 v92, -v216, v92, v107
	v_bfe_u32 v93, v92, 16, 1
	v_add3_u32 v92, v92, v93, s55
	ds_write_b16_d16_hi v9, v92 offset:4992
	v_mul_f32_e32 v92, v48, v12
	v_fma_f32 v4, -v216, v92, v4
	v_bfe_u32 v92, v4, 16, 1
	v_add3_u32 v4, v4, v92, s55
	ds_write_b16_d16_hi v9, v4 offset:6272
	v_mul_f32_e32 v4, v49, v13
	v_fma_f32 v4, -v216, v4, v5
	v_bfe_u32 v5, v4, 16, 1
	v_add3_u32 v4, v4, v5, s55
	ds_write_b16_d16_hi v9, v4 offset:6528
	v_mul_f32_e32 v4, v50, v10
	v_fma_f32 v4, -v216, v4, v6
	v_bfe_u32 v5, v4, 16, 1
	v_add3_u32 v4, v4, v5, s55
	ds_write_b16_d16_hi v9, v4 offset:6784
	v_mul_f32_e32 v4, v51, v11
	v_fma_f32 v4, -v216, v4, v7
	v_bfe_u32 v5, v4, 16, 1
	v_add3_u32 v4, v4, v5, s55
	ds_write_b16_d16_hi v9, v4 offset:7040
	v_mul_f32_e32 v4, v20, v90
	s_waitcnt vmcnt(2)
	v_fma_f32 v4, -v216, v4, v112
	v_bfe_u32 v5, v4, 16, 1
	v_add3_u32 v4, v4, v5, s55
	ds_write_b16_d16_hi v9, v4 offset:192
	v_mul_f32_e32 v4, v21, v91
	v_fma_f32 v4, -v216, v4, v113
	v_bfe_u32 v5, v4, 16, 1
	v_add3_u32 v4, v4, v5, s55
	ds_write_b16_d16_hi v9, v4 offset:448
	v_mul_f32_e32 v4, v22, v88
	v_fma_f32 v4, -v216, v4, v114
	v_bfe_u32 v5, v4, 16, 1
	v_add3_u32 v4, v4, v5, s55
	ds_write_b16_d16_hi v9, v4 offset:704
	v_mul_f32_e32 v4, v23, v89
	v_fma_f32 v4, -v216, v4, v115
	v_bfe_u32 v5, v4, 16, 1
	v_add3_u32 v4, v4, v5, s55
	ds_write_b16_d16_hi v9, v4 offset:960
	v_mul_f32_e32 v4, v24, v14
	v_fma_f32 v4, -v216, v4, v108
	v_bfe_u32 v5, v4, 16, 1
	v_add3_u32 v4, v4, v5, s55
	ds_write_b16_d16_hi v9, v4 offset:2240
	v_mul_f32_e32 v4, v25, v15
	v_fma_f32 v4, -v216, v4, v109
	v_bfe_u32 v5, v4, 16, 1
	v_add3_u32 v4, v4, v5, s55
	ds_write_b16_d16_hi v9, v4 offset:2496
	v_mul_f32_e32 v4, v26, v86
	v_fma_f32 v4, -v216, v4, v110
	v_bfe_u32 v5, v4, 16, 1
	v_add3_u32 v4, v4, v5, s55
	ds_write_b16_d16_hi v9, v4 offset:2752
	v_mul_f32_e32 v4, v27, v87
	v_fma_f32 v4, -v216, v4, v111
	v_bfe_u32 v5, v4, 16, 1
	v_add3_u32 v4, v4, v5, s55
	ds_write_b16_d16_hi v9, v4 offset:3008
	v_mul_f32_e32 v4, v28, v84
	s_waitcnt vmcnt(0)
; #define LAS __attribute__((address_space(3)))
; template <bool NOMAX>
; __device__ __forceinline__ void diff_unit(const AttnCtx& C, int u, LAS unsigned char* lds) {
;     ...
; #pragma unroll
;         for (int d = 0; d < 4; ++d)
; #pragma unroll
;             for (int gq = 0; gq < 4; ++gq) { const f32x4 s1 = st[d * 4 + gq];
; #pragma unroll
;                 for (int e = 0; e < 4; ++e) { const int r = 4 * gq + e; stg[crow(r, hi) * 128 + 32 * d + r32] = (bf16)f2bf(s1[e] - C.lam * (o[d][r] * rli[r])); } }
;         LDS_WAIT(); asm volatile("" ::: "memory");
;         const int cl = lanef & 15;
;         const size_t rowb = (size_t)(q0 + wid * 32);
; #pragma unroll
;         for (int ps = 0; ps < 8; ++ps) {
;             const int rl = ps * 4 + (lanef >> 4); const size_t row = rowb + rl;
;             const v4u sv = *(const LAS v4u*)(stg + rl * 128 + cl * 8);
;             float xv[8];
;             xv[0] = __builtin_bit_cast(float, sv.x << 16); xv[1] = __builtin_bit_cast(float, sv.x & 0xffff0000u); xv[2] = __builtin_bit_cast(float, sv.y << 16); xv[3] = __builtin_bit_cast(float, sv.y & 0xffff0000u);
;             xv[4] = __builtin_bit_cast(float, sv.z << 16); xv[5] = __builtin_bit_cast(float, sv.z & 0xffff0000u); xv[6] = __builtin_bit_cast(float, sv.w << 16); xv[7] = __builtin_bit_cast(float, sv.w & 0xffff0000u);
;             const v4u gv = *(const v4u*)(C.GD + row * 512 + h * 128 + cl * 8);
;             float gg[8];
;             gg[0] = __builtin_bit_cast(float, gv.x << 16); gg[1] = __builtin_bit_cast(float, gv.x & 0xffff0000u); gg[2] = __builtin_bit_cast(float, gv.y << 16); gg[3] = __builtin_bit_cast(float, gv.y & 0xffff0000u);
;             gg[4] = __builtin_bit_cast(float, gv.z << 16); gg[5] = __builtin_bit_cast(float, gv.z & 0xffff0000u); gg[6] = __builtin_bit_cast(float, gv.w << 16); gg[7] = __builtin_bit_cast(float, gv.w & 0xffff0000u);
;             float sq = 0.f;
; #pragma unroll
;             for (int e = 0; e < 8; ++e) sq += xv[e] * xv[e];
;     ...
;             SQDPP(0xB1); SQDPP(0x4E); SQDPP(0x141); SQDPP(0x140);
;     ...
;             const float rs = (1.0f / sqrtf(sq * (1.0f / 128.0f) + EPSN)) * 0.8f;
;             const f32x4 s0 = *(const f32x4*)(C.subln + cl * 8), s1 = *(const f32x4*)(C.subln + cl * 8 + 4);
; #pragma unroll
;             for (int e = 0; e < 4; ++e) { xv[e] *= rs * s0[e]; xv[4 + e] *= rs * s1[e]; }
	v_fma_f32 v4, -v216, v4, v100
	v_bfe_u32 v5, v4, 16, 1
	v_add3_u32 v4, v4, v5, s55
	ds_write_b16_d16_hi v9, v4 offset:4288
	v_mul_f32_e32 v4, v29, v85
	v_fma_f32 v4, -v216, v4, v101
	v_bfe_u32 v5, v4, 16, 1
	v_add3_u32 v4, v4, v5, s55
	ds_write_b16_d16_hi v9, v4 offset:4544
	v_mul_f32_e32 v4, v30, v16
	v_fma_f32 v4, -v216, v4, v102
	v_bfe_u32 v5, v4, 16, 1
	v_add3_u32 v4, v4, v5, s55
	ds_write_b16_d16_hi v9, v4 offset:4800
	v_mul_f32_e32 v4, v31, v17
	v_fma_f32 v4, -v216, v4, v103
	v_bfe_u32 v5, v4, 16, 1
	v_add3_u32 v4, v4, v5, s55
	ds_write_b16_d16_hi v9, v4 offset:5056
	v_mul_f32_e32 v4, v32, v12
	v_fma_f32 v4, -v216, v4, v96
	v_bfe_u32 v5, v4, 16, 1
	v_add3_u32 v4, v4, v5, s55
	ds_write_b16_d16_hi v9, v4 offset:6336
	v_mul_f32_e32 v4, v33, v13
	v_fma_f32 v4, -v216, v4, v97
	v_bfe_u32 v5, v4, 16, 1
	v_add3_u32 v4, v4, v5, s55
	ds_write_b16_d16_hi v9, v4 offset:6592
	v_mul_f32_e32 v4, v34, v10
	v_fma_f32 v4, -v216, v4, v98
	v_bfe_u32 v5, v4, 16, 1
	v_add3_u32 v4, v4, v5, s55
	ds_write_b16_d16_hi v9, v4 offset:6848
	v_mul_f32_e32 v4, v35, v11
	v_fma_f32 v4, -v216, v4, v99
	v_bfe_u32 v5, v4, 16, 1
	v_bfe_u32 v6, v8, 4, 2
	v_add3_u32 v4, v4, v5, s55
	v_or_b32_e32 v92, v202, v6
	v_mov_b32_e32 v93, v203
	ds_write_b16_d16_hi v9, v4 offset:7104
	v_lshlrev_b32_e32 v4, 3, v8
	v_lshlrev_b64 v[96:97], 10, v[92:93]
	v_and_b32_e32 v7, 0x78, v4
	v_lshl_add_u64 v[96:97], s[8:9], 0, v[96:97]
	s_waitcnt lgkmcnt(0)
	v_lshlrev_b32_e32 v4, 1, v7
	v_lshl_add_u64 v[96:97], v[96:97], 0, v[218:219]
	v_mov_b32_e32 v5, v3
	v_lshl_add_u64 v[96:97], v[96:97], 0, v[4:5]
	s_mov_b64 s[98:99], 0x1000
	v_lshl_add_u64 v[126:127], v[96:97], 0, s[98:99]
	global_load_dwordx4 v[128:131], v[126:127], off
	s_mov_b64 s[98:99], 0x2000
	v_lshl_add_u64 v[126:127], v[96:97], 0, s[98:99]
	global_load_dwordx4 v[132:135], v[126:127], off
	s_mov_b64 s[98:99], 0x3000
	v_lshl_add_u64 v[126:127], v[96:97], 0, s[98:99]
	global_load_dwordx4 v[136:139], v[126:127], off
	s_mov_b64 s[98:99], 0x4000
	v_lshl_add_u64 v[126:127], v[96:97], 0, s[98:99]
	global_load_dwordx4 v[140:143], v[126:127], off
	s_mov_b64 s[98:99], 0x5000
	v_lshl_add_u64 v[126:127], v[96:97], 0, s[98:99]
	global_load_dwordx4 v[144:147], v[126:127], off
	s_mov_b64 s[98:99], 0x6000
	v_lshl_add_u64 v[126:127], v[96:97], 0, s[98:99]
	global_load_dwordx4 v[148:151], v[126:127], off
	s_mov_b64 s[98:99], 0x7000
	v_lshl_add_u64 v[126:127], v[96:97], 0, s[98:99]
	global_load_dwordx4 v[152:155], v[126:127], off
	global_load_dwordx4 v[96:99], v[96:97], off
	v_lshlrev_b32_e32 v7, 2, v7
	global_load_dwordx4 v[100:103], v7, s[72:73]
	global_load_dwordx4 v[104:107], v7, s[72:73] offset:16
	v_add_u32_e32 v9, s0, v4
	v_lshl_add_u32 v95, v6, 8, v9
	ds_read_b128 v[108:111], v95
	v_lshlrev_b64 v[92:93], 11, v[92:93]
	v_lshl_add_u64 v[92:93], s[6:7], 0, v[92:93]
	v_lshl_add_u64 v[92:93], v[92:93], 0, v[218:219]
	v_lshl_add_u64 v[92:93], v[92:93], 0, v[4:5]
	s_waitcnt lgkmcnt(0)
	v_lshlrev_b32_e32 v124, 16, v108
	v_and_b32_e32 v125, 0xffff0000, v108
	v_lshlrev_b32_e32 v120, 16, v109
	v_and_b32_e32 v121, 0xffff0000, v109
	v_pk_mul_f32 v[108:109], v[124:125], v[124:125]
	v_pk_mul_f32 v[122:123], v[120:121], v[120:121]
	v_add_f32_e32 v95, v108, v109
	v_lshlrev_b32_e32 v118, 16, v110
	v_and_b32_e32 v119, 0xffff0000, v110
	v_add_f32_e32 v95, v122, v95
	v_lshlrev_b32_e32 v112, 16, v111
	v_and_b32_e32 v113, 0xffff0000, v111
	v_pk_mul_f32 v[110:111], v[118:119], v[118:119]
	v_add_f32_e32 v95, v123, v95
	v_add_f32_e32 v95, v110, v95
	v_pk_mul_f32 v[116:117], v[112:113], v[112:113]
	v_add_f32_e32 v95, v111, v95
	v_add_f32_e32 v95, v116, v95
	v_add_f32_e32 v95, v117, v95
	s_waitcnt vmcnt(2)
	v_lshlrev_b32_e32 v114, 16, v99
	v_add_f32_dpp v95, v95, v95 quad_perm:[1,0,3,2] row_mask:0xf bank_mask:0xf bound_ctrl:1
	v_and_b32_e32 v115, 0xffff0000, v99
	v_lshlrev_b32_e32 v108, 16, v98
	v_add_f32_dpp v95, v95, v95 quad_perm:[2,3,0,1] row_mask:0xf bank_mask:0xf bound_ctrl:1
	v_and_b32_e32 v109, 0xffff0000, v98
	v_lshlrev_b32_e32 v98, 16, v97
	v_add_f32_dpp v95, v95, v95 row_half_mirror row_mask:0xf bank_mask:0xf bound_ctrl:1
	s_nop 1
	v_add_f32_dpp v95, v95, v95 row_mirror row_mask:0xf bank_mask:0xf bound_ctrl:1
	v_fmamk_f32 v95, v95, 0x3c000000, v217
	v_mul_f32_e32 v99, 0x4f800000, v95
	v_cmp_gt_f32_e32 vcc, s56, v95
	s_nop 1
	v_cndmask_b32_e32 v95, v95, v99, vcc
	v_sqrt_f32_e32 v99, v95
	s_nop 0
	v_add_u32_e32 v110, -1, v99
	v_fma_f32 v111, -v110, v99, v95
	v_cmp_ge_f32_e64 s[4:5], 0, v111
	v_add_u32_e32 v111, 1, v99
	s_nop 0
	v_cndmask_b32_e64 v110, v99, v110, s[4:5]
	v_fma_f32 v99, -v111, v99, v95
	v_cmp_lt_f32_e64 s[4:5], 0, v99
	s_nop 1
	v_cndmask_b32_e64 v99, v110, v111, s[4:5]
	v_mul_f32_e32 v110, 0x37800000, v99
	v_cndmask_b32_e32 v99, v99, v110, vcc
	v_cmp_class_f32_e32 vcc, v95, v228
	v_lshlrev_b32_e32 v110, 16, v96
	v_and_b32_e32 v111, 0xffff0000, v96
	v_cndmask_b32_e32 v95, v99, v95, vcc
	v_div_scale_f32 v116, s[0:1], v95, v95, 1.0
	v_rcp_f32_e32 v117, v116
	v_and_b32_e32 v99, 0xffff0000, v97
	v_fma_f32 v96, -v116, v117, 1.0
	v_fmac_f32_e32 v117, v96, v117
	v_div_scale_f32 v96, vcc, 1.0, v95, 1.0
	v_mul_f32_e32 v97, v96, v117
	v_fma_f32 v122, -v116, v97, v96
	v_fmac_f32_e32 v97, v122, v117
	v_fma_f32 v96, -v116, v97, v96
	v_div_fmas_f32 v96, v96, v117, v97
	v_div_fixup_f32 v95, v96, v95, 1.0
	v_mul_f32_e32 v96, 0x3f4ccccd, v95
	s_waitcnt vmcnt(1)
	v_pk_mul_f32 v[100:101], v[100:101], v[96:97] op_sel_hi:[1,0]
	v_pk_mul_f32 v[102:103], v[102:103], v[96:97] op_sel_hi:[1,0]
	v_pk_mul_f32 v[100:101], v[100:101], v[124:125]
	s_waitcnt vmcnt(0)
; #define LAS __attribute__((address_space(3)))
; __device__ __forceinline__ unsigned pk2(float lo, float hi) { f32x2_t v = {lo, hi}; bf16x2_t b = __builtin_convertvector(v, bf16x2_t); return __builtin_bit_cast(unsigned, b); }
; template <bool NOMAX>
; __device__ __forceinline__ void diff_unit(const AttnCtx& C, int u, LAS unsigned char* lds) {
;     ...
;         for (int ps = 0; ps < 8; ++ps) {
;             const int rl = ps * 4 + (lanef >> 4); const size_t row = rowb + rl;
;             const v4u sv = *(const LAS v4u*)(stg + rl * 128 + cl * 8);
;             float xv[8];
;             xv[0] = __builtin_bit_cast(float, sv.x << 16); xv[1] = __builtin_bit_cast(float, sv.x & 0xffff0000u); xv[2] = __builtin_bit_cast(float, sv.y << 16); xv[3] = __builtin_bit_cast(float, sv.y & 0xffff0000u);
;             xv[4] = __builtin_bit_cast(float, sv.z << 16); xv[5] = __builtin_bit_cast(float, sv.z & 0xffff0000u); xv[6] = __builtin_bit_cast(float, sv.w << 16); xv[7] = __builtin_bit_cast(float, sv.w & 0xffff0000u);
;             const v4u gv = *(const v4u*)(C.GD + row * 512 + h * 128 + cl * 8);
;             float gg[8];
;             gg[0] = __builtin_bit_cast(float, gv.x << 16); gg[1] = __builtin_bit_cast(float, gv.x & 0xffff0000u); gg[2] = __builtin_bit_cast(float, gv.y << 16); gg[3] = __builtin_bit_cast(float, gv.y & 0xffff0000u);
;             gg[4] = __builtin_bit_cast(float, gv.z << 16); gg[5] = __builtin_bit_cast(float, gv.z & 0xffff0000u); gg[6] = __builtin_bit_cast(float, gv.w << 16); gg[7] = __builtin_bit_cast(float, gv.w & 0xffff0000u);
;             float sq = 0.f;
; #pragma unroll
;             for (int e = 0; e < 8; ++e) sq += xv[e] * xv[e];
;     ...
;             SQDPP(0xB1); SQDPP(0x4E); SQDPP(0x141); SQDPP(0x140);
;     ...
;             const float rs = (1.0f / sqrtf(sq * (1.0f / 128.0f) + EPSN)) * 0.8f;
;             const f32x4 s0 = *(const f32x4*)(C.subln + cl * 8), s1 = *(const f32x4*)(C.subln + cl * 8 + 4);
; #pragma unroll
;             for (int e = 0; e < 4; ++e) { xv[e] *= rs * s0[e]; xv[4 + e] *= rs * s1[e]; }
;             v4u ov; ov.x = pk2(xv[0] * gg[0], xv[1] * gg[1]); ov.y = pk2(xv[2] * gg[2], xv[3] * gg[3]); ov.z = pk2(xv[4] * gg[4], xv[5] * gg[5]); ov.w = pk2(xv[6] * gg[6], xv[7] * gg[7]);
;             *(v4u*)(C.MIX + row * 1024 + 512 + h * 128 + cl * 8) = ov;
	v_pk_mul_f32 v[104:105], v[104:105], v[96:97] op_sel_hi:[1,0]
	v_pk_mul_f32 v[102:103], v[102:103], v[120:121]
	v_pk_mul_f32 v[96:97], v[106:107], v[96:97] op_sel_hi:[1,0]
	v_pk_mul_f32 v[104:105], v[104:105], v[118:119]
	v_pk_mul_f32 v[106:107], v[96:97], v[112:113]
	v_pk_mul_f32 v[96:97], v[100:101], v[110:111]
	v_pk_mul_f32 v[98:99], v[102:103], v[98:99]
	v_cvt_pk_bf16_f32 v96, v96, v97
	v_cvt_pk_bf16_f32 v97, v98, v99
	v_pk_mul_f32 v[98:99], v[104:105], v[108:109]
	v_pk_mul_f32 v[100:101], v[106:107], v[114:115]
	v_cvt_pk_bf16_f32 v98, v98, v99
	v_cvt_pk_bf16_f32 v99, v100, v101
	v_or_b32_e32 v95, 4, v6
	global_store_dwordx4 v[92:93], v[96:99], off offset:1024
	v_or_b32_e32 v92, v202, v95
	v_mov_b32_e32 v93, v203
	global_load_dwordx4 v[100:103], v7, s[72:73]
	global_load_dwordx4 v[104:107], v7, s[72:73] offset:16
	v_lshl_add_u32 v95, v95, 8, v9
	ds_read_b128 v[108:111], v95
	v_lshlrev_b64 v[92:93], 11, v[92:93]
	v_lshl_add_u64 v[92:93], s[6:7], 0, v[92:93]
	v_lshl_add_u64 v[92:93], v[92:93], 0, v[218:219]
	v_lshl_add_u64 v[92:93], v[92:93], 0, v[4:5]
	s_waitcnt lgkmcnt(0)
	v_lshlrev_b32_e32 v124, 16, v108
	v_and_b32_e32 v125, 0xffff0000, v108
	v_lshlrev_b32_e32 v120, 16, v109
	v_and_b32_e32 v121, 0xffff0000, v109
	v_pk_mul_f32 v[108:109], v[124:125], v[124:125]
	v_pk_mul_f32 v[122:123], v[120:121], v[120:121]
	v_add_f32_e32 v95, v108, v109
	v_lshlrev_b32_e32 v118, 16, v110
	v_and_b32_e32 v119, 0xffff0000, v110
	v_add_f32_e32 v95, v122, v95
	v_lshlrev_b32_e32 v112, 16, v111
	v_and_b32_e32 v113, 0xffff0000, v111
	v_pk_mul_f32 v[110:111], v[118:119], v[118:119]
	v_add_f32_e32 v95, v123, v95
	v_add_f32_e32 v95, v110, v95
	v_pk_mul_f32 v[116:117], v[112:113], v[112:113]
	v_add_f32_e32 v95, v111, v95
	v_add_f32_e32 v95, v116, v95
	v_add_f32_e32 v95, v117, v95
	s_waitcnt vmcnt(2)
	v_lshlrev_b32_e32 v114, 16, v131
	v_add_f32_dpp v95, v95, v95 quad_perm:[1,0,3,2] row_mask:0xf bank_mask:0xf bound_ctrl:1
	v_and_b32_e32 v115, 0xffff0000, v131
	v_lshlrev_b32_e32 v108, 16, v130
	v_add_f32_dpp v95, v95, v95 quad_perm:[2,3,0,1] row_mask:0xf bank_mask:0xf bound_ctrl:1
	v_and_b32_e32 v109, 0xffff0000, v130
	v_lshlrev_b32_e32 v98, 16, v129
	v_add_f32_dpp v95, v95, v95 row_half_mirror row_mask:0xf bank_mask:0xf bound_ctrl:1
	s_nop 1
	v_add_f32_dpp v95, v95, v95 row_mirror row_mask:0xf bank_mask:0xf bound_ctrl:1
	v_fmamk_f32 v95, v95, 0x3c000000, v217
	v_mul_f32_e32 v99, 0x4f800000, v95
	v_cmp_gt_f32_e32 vcc, s56, v95
	s_nop 1
	v_cndmask_b32_e32 v95, v95, v99, vcc
	v_sqrt_f32_e32 v99, v95
	s_nop 0
	v_add_u32_e32 v110, -1, v99
	v_fma_f32 v111, -v110, v99, v95
	v_cmp_ge_f32_e64 s[4:5], 0, v111
	v_add_u32_e32 v111, 1, v99
	s_nop 0
	v_cndmask_b32_e64 v110, v99, v110, s[4:5]
	v_fma_f32 v99, -v111, v99, v95
	v_cmp_lt_f32_e64 s[4:5], 0, v99
	s_nop 1
	v_cndmask_b32_e64 v99, v110, v111, s[4:5]
	v_mul_f32_e32 v110, 0x37800000, v99
	v_cndmask_b32_e32 v99, v99, v110, vcc
	v_cmp_class_f32_e32 vcc, v95, v228
	v_lshlrev_b32_e32 v110, 16, v128
	v_and_b32_e32 v111, 0xffff0000, v128
	v_cndmask_b32_e32 v95, v99, v95, vcc
	v_div_scale_f32 v116, s[0:1], v95, v95, 1.0
	v_rcp_f32_e32 v117, v116
	v_and_b32_e32 v99, 0xffff0000, v129
	v_fma_f32 v96, -v116, v117, 1.0
	v_fmac_f32_e32 v117, v96, v117
	v_div_scale_f32 v96, vcc, 1.0, v95, 1.0
	v_mul_f32_e32 v97, v96, v117
	v_fma_f32 v122, -v116, v97, v96
	v_fmac_f32_e32 v97, v122, v117
	v_fma_f32 v96, -v116, v97, v96
	v_div_fmas_f32 v96, v96, v117, v97
	v_div_fixup_f32 v95, v96, v95, 1.0
	v_mul_f32_e32 v96, 0x3f4ccccd, v95
	s_waitcnt vmcnt(1)
	v_pk_mul_f32 v[100:101], v[100:101], v[96:97] op_sel_hi:[1,0]
	v_pk_mul_f32 v[102:103], v[102:103], v[96:97] op_sel_hi:[1,0]
	v_pk_mul_f32 v[100:101], v[100:101], v[124:125]
	s_waitcnt vmcnt(0)
	v_pk_mul_f32 v[104:105], v[104:105], v[96:97] op_sel_hi:[1,0]
	v_pk_mul_f32 v[102:103], v[102:103], v[120:121]
	v_pk_mul_f32 v[96:97], v[106:107], v[96:97] op_sel_hi:[1,0]
	v_pk_mul_f32 v[104:105], v[104:105], v[118:119]
	v_pk_mul_f32 v[106:107], v[96:97], v[112:113]
	v_pk_mul_f32 v[96:97], v[100:101], v[110:111]
	v_pk_mul_f32 v[98:99], v[102:103], v[98:99]
	v_cvt_pk_bf16_f32 v96, v96, v97
	v_cvt_pk_bf16_f32 v97, v98, v99
	v_pk_mul_f32 v[98:99], v[104:105], v[108:109]
	v_pk_mul_f32 v[100:101], v[106:107], v[114:115]
	v_cvt_pk_bf16_f32 v98, v98, v99
	v_cvt_pk_bf16_f32 v99, v100, v101
	v_or_b32_e32 v95, 8, v6
	global_store_dwordx4 v[92:93], v[96:99], off offset:1024
	v_or_b32_e32 v92, v202, v95
	v_mov_b32_e32 v93, v203
	global_load_dwordx4 v[100:103], v7, s[72:73]
	global_load_dwordx4 v[104:107], v7, s[72:73] offset:16
	v_lshl_add_u32 v95, v95, 8, v9
	ds_read_b128 v[108:111], v95
	v_lshlrev_b64 v[92:93], 11, v[92:93]
	v_lshl_add_u64 v[92:93], s[6:7], 0, v[92:93]
	v_lshl_add_u64 v[92:93], v[92:93], 0, v[218:219]
	v_lshl_add_u64 v[92:93], v[92:93], 0, v[4:5]
	s_waitcnt lgkmcnt(0)
	v_lshlrev_b32_e32 v124, 16, v108
	v_and_b32_e32 v125, 0xffff0000, v108
	v_lshlrev_b32_e32 v120, 16, v109
	v_and_b32_e32 v121, 0xffff0000, v109
	v_pk_mul_f32 v[108:109], v[124:125], v[124:125]
	v_pk_mul_f32 v[122:123], v[120:121], v[120:121]
	v_add_f32_e32 v95, v108, v109
	v_lshlrev_b32_e32 v118, 16, v110
	v_and_b32_e32 v119, 0xffff0000, v110
	v_add_f32_e32 v95, v122, v95
	v_lshlrev_b32_e32 v112, 16, v111
	v_and_b32_e32 v113, 0xffff0000, v111
	v_pk_mul_f32 v[110:111], v[118:119], v[118:119]
	v_add_f32_e32 v95, v123, v95
	v_add_f32_e32 v95, v110, v95
	v_pk_mul_f32 v[116:117], v[112:113], v[112:113]
	v_add_f32_e32 v95, v111, v95
	v_add_f32_e32 v95, v116, v95
	v_add_f32_e32 v95, v117, v95
	s_waitcnt vmcnt(2)
; #define LAS __attribute__((address_space(3)))
; __device__ __forceinline__ unsigned pk2(float lo, float hi) { f32x2_t v = {lo, hi}; bf16x2_t b = __builtin_convertvector(v, bf16x2_t); return __builtin_bit_cast(unsigned, b); }
; template <bool NOMAX>
; __device__ __forceinline__ void diff_unit(const AttnCtx& C, int u, LAS unsigned char* lds) {
;     ...
;         for (int ps = 0; ps < 8; ++ps) {
;             const int rl = ps * 4 + (lanef >> 4); const size_t row = rowb + rl;
;             const v4u sv = *(const LAS v4u*)(stg + rl * 128 + cl * 8);
;             float xv[8];
;             xv[0] = __builtin_bit_cast(float, sv.x << 16); xv[1] = __builtin_bit_cast(float, sv.x & 0xffff0000u); xv[2] = __builtin_bit_cast(float, sv.y << 16); xv[3] = __builtin_bit_cast(float, sv.y & 0xffff0000u);
;             xv[4] = __builtin_bit_cast(float, sv.z << 16); xv[5] = __builtin_bit_cast(float, sv.z & 0xffff0000u); xv[6] = __builtin_bit_cast(float, sv.w << 16); xv[7] = __builtin_bit_cast(float, sv.w & 0xffff0000u);
;             const v4u gv = *(const v4u*)(C.GD + row * 512 + h * 128 + cl * 8);
;             float gg[8];
;             gg[0] = __builtin_bit_cast(float, gv.x << 16); gg[1] = __builtin_bit_cast(float, gv.x & 0xffff0000u); gg[2] = __builtin_bit_cast(float, gv.y << 16); gg[3] = __builtin_bit_cast(float, gv.y & 0xffff0000u);
;             gg[4] = __builtin_bit_cast(float, gv.z << 16); gg[5] = __builtin_bit_cast(float, gv.z & 0xffff0000u); gg[6] = __builtin_bit_cast(float, gv.w << 16); gg[7] = __builtin_bit_cast(float, gv.w & 0xffff0000u);
;             float sq = 0.f;
; #pragma unroll
;             for (int e = 0; e < 8; ++e) sq += xv[e] * xv[e];
;     ...
;             SQDPP(0xB1); SQDPP(0x4E); SQDPP(0x141); SQDPP(0x140);
;     ...
;             const float rs = (1.0f / sqrtf(sq * (1.0f / 128.0f) + EPSN)) * 0.8f;
;             const f32x4 s0 = *(const f32x4*)(C.subln + cl * 8), s1 = *(const f32x4*)(C.subln + cl * 8 + 4);
; #pragma unroll
;             for (int e = 0; e < 4; ++e) { xv[e] *= rs * s0[e]; xv[4 + e] *= rs * s1[e]; }
;             v4u ov; ov.x = pk2(xv[0] * gg[0], xv[1] * gg[1]); ov.y = pk2(xv[2] * gg[2], xv[3] * gg[3]); ov.z = pk2(xv[4] * gg[4], xv[5] * gg[5]); ov.w = pk2(xv[6] * gg[6], xv[7] * gg[7]);
;             *(v4u*)(C.MIX + row * 1024 + 512 + h * 128 + cl * 8) = ov;
	v_lshlrev_b32_e32 v114, 16, v135
	v_add_f32_dpp v95, v95, v95 quad_perm:[1,0,3,2] row_mask:0xf bank_mask:0xf bound_ctrl:1
	v_and_b32_e32 v115, 0xffff0000, v135
	v_lshlrev_b32_e32 v108, 16, v134
	v_add_f32_dpp v95, v95, v95 quad_perm:[2,3,0,1] row_mask:0xf bank_mask:0xf bound_ctrl:1
	v_and_b32_e32 v109, 0xffff0000, v134
	v_lshlrev_b32_e32 v98, 16, v133
	v_add_f32_dpp v95, v95, v95 row_half_mirror row_mask:0xf bank_mask:0xf bound_ctrl:1
	s_nop 1
	v_add_f32_dpp v95, v95, v95 row_mirror row_mask:0xf bank_mask:0xf bound_ctrl:1
	v_fmamk_f32 v95, v95, 0x3c000000, v217
	v_mul_f32_e32 v99, 0x4f800000, v95
	v_cmp_gt_f32_e32 vcc, s56, v95
	s_nop 1
	v_cndmask_b32_e32 v95, v95, v99, vcc
	v_sqrt_f32_e32 v99, v95
	s_nop 0
	v_add_u32_e32 v110, -1, v99
	v_fma_f32 v111, -v110, v99, v95
	v_cmp_ge_f32_e64 s[4:5], 0, v111
	v_add_u32_e32 v111, 1, v99
	s_nop 0
	v_cndmask_b32_e64 v110, v99, v110, s[4:5]
	v_fma_f32 v99, -v111, v99, v95
	v_cmp_lt_f32_e64 s[4:5], 0, v99
	s_nop 1
	v_cndmask_b32_e64 v99, v110, v111, s[4:5]
	v_mul_f32_e32 v110, 0x37800000, v99
	v_cndmask_b32_e32 v99, v99, v110, vcc
	v_cmp_class_f32_e32 vcc, v95, v228
	v_lshlrev_b32_e32 v110, 16, v132
	v_and_b32_e32 v111, 0xffff0000, v132
	v_cndmask_b32_e32 v95, v99, v95, vcc
	v_div_scale_f32 v116, s[0:1], v95, v95, 1.0
	v_rcp_f32_e32 v117, v116
	v_and_b32_e32 v99, 0xffff0000, v133
	v_fma_f32 v96, -v116, v117, 1.0
	v_fmac_f32_e32 v117, v96, v117
	v_div_scale_f32 v96, vcc, 1.0, v95, 1.0
	v_mul_f32_e32 v97, v96, v117
	v_fma_f32 v122, -v116, v97, v96
	v_fmac_f32_e32 v97, v122, v117
	v_fma_f32 v96, -v116, v97, v96
	v_div_fmas_f32 v96, v96, v117, v97
	v_div_fixup_f32 v95, v96, v95, 1.0
	v_mul_f32_e32 v96, 0x3f4ccccd, v95
	s_waitcnt vmcnt(1)
	v_pk_mul_f32 v[100:101], v[100:101], v[96:97] op_sel_hi:[1,0]
	v_pk_mul_f32 v[102:103], v[102:103], v[96:97] op_sel_hi:[1,0]
	v_pk_mul_f32 v[100:101], v[100:101], v[124:125]
	s_waitcnt vmcnt(0)
	v_pk_mul_f32 v[104:105], v[104:105], v[96:97] op_sel_hi:[1,0]
	v_pk_mul_f32 v[102:103], v[102:103], v[120:121]
	v_pk_mul_f32 v[96:97], v[106:107], v[96:97] op_sel_hi:[1,0]
	v_pk_mul_f32 v[104:105], v[104:105], v[118:119]
	v_pk_mul_f32 v[106:107], v[96:97], v[112:113]
	v_pk_mul_f32 v[96:97], v[100:101], v[110:111]
	v_pk_mul_f32 v[98:99], v[102:103], v[98:99]
	v_cvt_pk_bf16_f32 v96, v96, v97
	v_cvt_pk_bf16_f32 v97, v98, v99
	v_pk_mul_f32 v[98:99], v[104:105], v[108:109]
	v_pk_mul_f32 v[100:101], v[106:107], v[114:115]
	v_cvt_pk_bf16_f32 v98, v98, v99
	v_cvt_pk_bf16_f32 v99, v100, v101
	v_or_b32_e32 v95, 12, v6
	global_store_dwordx4 v[92:93], v[96:99], off offset:1024
	v_or_b32_e32 v92, v202, v95
	v_mov_b32_e32 v93, v203
	global_load_dwordx4 v[100:103], v7, s[72:73]
	global_load_dwordx4 v[104:107], v7, s[72:73] offset:16
	v_lshl_add_u32 v95, v95, 8, v9
	ds_read_b128 v[108:111], v95
	v_lshlrev_b64 v[92:93], 11, v[92:93]
	v_lshl_add_u64 v[92:93], s[6:7], 0, v[92:93]
	v_lshl_add_u64 v[92:93], v[92:93], 0, v[218:219]
	v_lshl_add_u64 v[92:93], v[92:93], 0, v[4:5]
	s_waitcnt lgkmcnt(0)
	v_lshlrev_b32_e32 v124, 16, v108
	v_and_b32_e32 v125, 0xffff0000, v108
	v_lshlrev_b32_e32 v120, 16, v109
	v_and_b32_e32 v121, 0xffff0000, v109
	v_pk_mul_f32 v[108:109], v[124:125], v[124:125]
	v_pk_mul_f32 v[122:123], v[120:121], v[120:121]
	v_add_f32_e32 v95, v108, v109
	v_lshlrev_b32_e32 v118, 16, v110
	v_and_b32_e32 v119, 0xffff0000, v110
	v_add_f32_e32 v95, v122, v95
	v_lshlrev_b32_e32 v112, 16, v111
	v_and_b32_e32 v113, 0xffff0000, v111
	v_pk_mul_f32 v[110:111], v[118:119], v[118:119]
	v_add_f32_e32 v95, v123, v95
	v_add_f32_e32 v95, v110, v95
	v_pk_mul_f32 v[116:117], v[112:113], v[112:113]
	v_add_f32_e32 v95, v111, v95
	v_add_f32_e32 v95, v116, v95
	v_add_f32_e32 v95, v117, v95
	s_waitcnt vmcnt(2)
	v_lshlrev_b32_e32 v114, 16, v139
	v_add_f32_dpp v95, v95, v95 quad_perm:[1,0,3,2] row_mask:0xf bank_mask:0xf bound_ctrl:1
	v_and_b32_e32 v115, 0xffff0000, v139
	v_lshlrev_b32_e32 v108, 16, v138
	v_add_f32_dpp v95, v95, v95 quad_perm:[2,3,0,1] row_mask:0xf bank_mask:0xf bound_ctrl:1
	v_and_b32_e32 v109, 0xffff0000, v138
	v_lshlrev_b32_e32 v98, 16, v137
	v_add_f32_dpp v95, v95, v95 row_half_mirror row_mask:0xf bank_mask:0xf bound_ctrl:1
	s_nop 1
	v_add_f32_dpp v95, v95, v95 row_mirror row_mask:0xf bank_mask:0xf bound_ctrl:1
	v_fmamk_f32 v95, v95, 0x3c000000, v217
	v_mul_f32_e32 v99, 0x4f800000, v95
	v_cmp_gt_f32_e32 vcc, s56, v95
	s_nop 1
	v_cndmask_b32_e32 v95, v95, v99, vcc
	v_sqrt_f32_e32 v99, v95
	s_nop 0
	v_add_u32_e32 v110, -1, v99
	v_fma_f32 v111, -v110, v99, v95
	v_cmp_ge_f32_e64 s[4:5], 0, v111
	v_add_u32_e32 v111, 1, v99
	s_nop 0
	v_cndmask_b32_e64 v110, v99, v110, s[4:5]
	v_fma_f32 v99, -v111, v99, v95
	v_cmp_lt_f32_e64 s[4:5], 0, v99
	s_nop 1
	v_cndmask_b32_e64 v99, v110, v111, s[4:5]
	v_mul_f32_e32 v110, 0x37800000, v99
	v_cndmask_b32_e32 v99, v99, v110, vcc
	v_cmp_class_f32_e32 vcc, v95, v228
	v_lshlrev_b32_e32 v110, 16, v136
	v_and_b32_e32 v111, 0xffff0000, v136
	v_cndmask_b32_e32 v95, v99, v95, vcc
	v_div_scale_f32 v116, s[0:1], v95, v95, 1.0
	v_rcp_f32_e32 v117, v116
	v_and_b32_e32 v99, 0xffff0000, v137
	v_fma_f32 v96, -v116, v117, 1.0
	v_fmac_f32_e32 v117, v96, v117
	v_div_scale_f32 v96, vcc, 1.0, v95, 1.0
	v_mul_f32_e32 v97, v96, v117
	v_fma_f32 v122, -v116, v97, v96
	v_fmac_f32_e32 v97, v122, v117
	v_fma_f32 v96, -v116, v97, v96
	v_div_fmas_f32 v96, v96, v117, v97
	v_div_fixup_f32 v95, v96, v95, 1.0
	v_mul_f32_e32 v96, 0x3f4ccccd, v95
	s_waitcnt vmcnt(1)
	v_pk_mul_f32 v[100:101], v[100:101], v[96:97] op_sel_hi:[1,0]
	v_pk_mul_f32 v[102:103], v[102:103], v[96:97] op_sel_hi:[1,0]
	v_pk_mul_f32 v[100:101], v[100:101], v[124:125]
	s_waitcnt vmcnt(0)
; #define LAS __attribute__((address_space(3)))
; __device__ __forceinline__ unsigned pk2(float lo, float hi) { f32x2_t v = {lo, hi}; bf16x2_t b = __builtin_convertvector(v, bf16x2_t); return __builtin_bit_cast(unsigned, b); }
; template <bool NOMAX>
; __device__ __forceinline__ void diff_unit(const AttnCtx& C, int u, LAS unsigned char* lds) {
;     ...
;         for (int ps = 0; ps < 8; ++ps) {
;             const int rl = ps * 4 + (lanef >> 4); const size_t row = rowb + rl;
;             const v4u sv = *(const LAS v4u*)(stg + rl * 128 + cl * 8);
;             float xv[8];
;             xv[0] = __builtin_bit_cast(float, sv.x << 16); xv[1] = __builtin_bit_cast(float, sv.x & 0xffff0000u); xv[2] = __builtin_bit_cast(float, sv.y << 16); xv[3] = __builtin_bit_cast(float, sv.y & 0xffff0000u);
;             xv[4] = __builtin_bit_cast(float, sv.z << 16); xv[5] = __builtin_bit_cast(float, sv.z & 0xffff0000u); xv[6] = __builtin_bit_cast(float, sv.w << 16); xv[7] = __builtin_bit_cast(float, sv.w & 0xffff0000u);
;             const v4u gv = *(const v4u*)(C.GD + row * 512 + h * 128 + cl * 8);
;             float gg[8];
;             gg[0] = __builtin_bit_cast(float, gv.x << 16); gg[1] = __builtin_bit_cast(float, gv.x & 0xffff0000u); gg[2] = __builtin_bit_cast(float, gv.y << 16); gg[3] = __builtin_bit_cast(float, gv.y & 0xffff0000u);
;             gg[4] = __builtin_bit_cast(float, gv.z << 16); gg[5] = __builtin_bit_cast(float, gv.z & 0xffff0000u); gg[6] = __builtin_bit_cast(float, gv.w << 16); gg[7] = __builtin_bit_cast(float, gv.w & 0xffff0000u);
;             float sq = 0.f;
; #pragma unroll
;             for (int e = 0; e < 8; ++e) sq += xv[e] * xv[e];
;     ...
;             SQDPP(0xB1); SQDPP(0x4E); SQDPP(0x141); SQDPP(0x140);
;     ...
;             const float rs = (1.0f / sqrtf(sq * (1.0f / 128.0f) + EPSN)) * 0.8f;
;             const f32x4 s0 = *(const f32x4*)(C.subln + cl * 8), s1 = *(const f32x4*)(C.subln + cl * 8 + 4);
; #pragma unroll
;             for (int e = 0; e < 4; ++e) { xv[e] *= rs * s0[e]; xv[4 + e] *= rs * s1[e]; }
;             v4u ov; ov.x = pk2(xv[0] * gg[0], xv[1] * gg[1]); ov.y = pk2(xv[2] * gg[2], xv[3] * gg[3]); ov.z = pk2(xv[4] * gg[4], xv[5] * gg[5]); ov.w = pk2(xv[6] * gg[6], xv[7] * gg[7]);
;             *(v4u*)(C.MIX + row * 1024 + 512 + h * 128 + cl * 8) = ov;
	v_pk_mul_f32 v[104:105], v[104:105], v[96:97] op_sel_hi:[1,0]
	v_pk_mul_f32 v[102:103], v[102:103], v[120:121]
	v_pk_mul_f32 v[96:97], v[106:107], v[96:97] op_sel_hi:[1,0]
	v_pk_mul_f32 v[104:105], v[104:105], v[118:119]
	v_pk_mul_f32 v[106:107], v[96:97], v[112:113]
	v_pk_mul_f32 v[96:97], v[100:101], v[110:111]
	v_pk_mul_f32 v[98:99], v[102:103], v[98:99]
	v_cvt_pk_bf16_f32 v96, v96, v97
	v_cvt_pk_bf16_f32 v97, v98, v99
	v_pk_mul_f32 v[98:99], v[104:105], v[108:109]
	v_pk_mul_f32 v[100:101], v[106:107], v[114:115]
	v_cvt_pk_bf16_f32 v98, v98, v99
	v_cvt_pk_bf16_f32 v99, v100, v101
	v_or_b32_e32 v95, 16, v6
	global_store_dwordx4 v[92:93], v[96:99], off offset:1024
	v_or_b32_e32 v92, v202, v95
	v_mov_b32_e32 v93, v203
	global_load_dwordx4 v[100:103], v7, s[72:73]
	global_load_dwordx4 v[104:107], v7, s[72:73] offset:16
	v_lshl_add_u32 v95, v95, 8, v9
	ds_read_b128 v[108:111], v95
	v_lshlrev_b64 v[92:93], 11, v[92:93]
	v_lshl_add_u64 v[92:93], s[6:7], 0, v[92:93]
	v_lshl_add_u64 v[92:93], v[92:93], 0, v[218:219]
	v_lshl_add_u64 v[92:93], v[92:93], 0, v[4:5]
	s_waitcnt lgkmcnt(0)
	v_lshlrev_b32_e32 v124, 16, v108
	v_and_b32_e32 v125, 0xffff0000, v108
	v_lshlrev_b32_e32 v120, 16, v109
	v_and_b32_e32 v121, 0xffff0000, v109
	v_pk_mul_f32 v[108:109], v[124:125], v[124:125]
	v_pk_mul_f32 v[122:123], v[120:121], v[120:121]
	v_add_f32_e32 v95, v108, v109
	v_lshlrev_b32_e32 v118, 16, v110
	v_and_b32_e32 v119, 0xffff0000, v110
	v_add_f32_e32 v95, v122, v95
	v_lshlrev_b32_e32 v112, 16, v111
	v_and_b32_e32 v113, 0xffff0000, v111
	v_pk_mul_f32 v[110:111], v[118:119], v[118:119]
	v_add_f32_e32 v95, v123, v95
	v_add_f32_e32 v95, v110, v95
	v_pk_mul_f32 v[116:117], v[112:113], v[112:113]
	v_add_f32_e32 v95, v111, v95
	v_add_f32_e32 v95, v116, v95
	v_add_f32_e32 v95, v117, v95
	s_waitcnt vmcnt(2)
	v_lshlrev_b32_e32 v114, 16, v143
	v_add_f32_dpp v95, v95, v95 quad_perm:[1,0,3,2] row_mask:0xf bank_mask:0xf bound_ctrl:1
	v_and_b32_e32 v115, 0xffff0000, v143
	v_lshlrev_b32_e32 v108, 16, v142
	v_add_f32_dpp v95, v95, v95 quad_perm:[2,3,0,1] row_mask:0xf bank_mask:0xf bound_ctrl:1
	v_and_b32_e32 v109, 0xffff0000, v142
	v_lshlrev_b32_e32 v98, 16, v141
	v_add_f32_dpp v95, v95, v95 row_half_mirror row_mask:0xf bank_mask:0xf bound_ctrl:1
	s_nop 1
	v_add_f32_dpp v95, v95, v95 row_mirror row_mask:0xf bank_mask:0xf bound_ctrl:1
	v_fmamk_f32 v95, v95, 0x3c000000, v217
	v_mul_f32_e32 v99, 0x4f800000, v95
	v_cmp_gt_f32_e32 vcc, s56, v95
	s_nop 1
	v_cndmask_b32_e32 v95, v95, v99, vcc
	v_sqrt_f32_e32 v99, v95
	s_nop 0
	v_add_u32_e32 v110, -1, v99
	v_fma_f32 v111, -v110, v99, v95
	v_cmp_ge_f32_e64 s[4:5], 0, v111
	v_add_u32_e32 v111, 1, v99
	s_nop 0
	v_cndmask_b32_e64 v110, v99, v110, s[4:5]
	v_fma_f32 v99, -v111, v99, v95
	v_cmp_lt_f32_e64 s[4:5], 0, v99
	s_nop 1
	v_cndmask_b32_e64 v99, v110, v111, s[4:5]
	v_mul_f32_e32 v110, 0x37800000, v99
	v_cndmask_b32_e32 v99, v99, v110, vcc
	v_cmp_class_f32_e32 vcc, v95, v228
	v_lshlrev_b32_e32 v110, 16, v140
	v_and_b32_e32 v111, 0xffff0000, v140
	v_cndmask_b32_e32 v95, v99, v95, vcc
	v_div_scale_f32 v116, s[0:1], v95, v95, 1.0
	v_rcp_f32_e32 v117, v116
	v_and_b32_e32 v99, 0xffff0000, v141
	v_fma_f32 v96, -v116, v117, 1.0
	v_fmac_f32_e32 v117, v96, v117
	v_div_scale_f32 v96, vcc, 1.0, v95, 1.0
	v_mul_f32_e32 v97, v96, v117
	v_fma_f32 v122, -v116, v97, v96
	v_fmac_f32_e32 v97, v122, v117
	v_fma_f32 v96, -v116, v97, v96
	v_div_fmas_f32 v96, v96, v117, v97
	v_div_fixup_f32 v95, v96, v95, 1.0
	v_mul_f32_e32 v96, 0x3f4ccccd, v95
	s_waitcnt vmcnt(1)
	v_pk_mul_f32 v[100:101], v[100:101], v[96:97] op_sel_hi:[1,0]
	v_pk_mul_f32 v[102:103], v[102:103], v[96:97] op_sel_hi:[1,0]
	v_pk_mul_f32 v[100:101], v[100:101], v[124:125]
	s_waitcnt vmcnt(0)
	v_pk_mul_f32 v[104:105], v[104:105], v[96:97] op_sel_hi:[1,0]
	v_pk_mul_f32 v[102:103], v[102:103], v[120:121]
	v_pk_mul_f32 v[96:97], v[106:107], v[96:97] op_sel_hi:[1,0]
	v_pk_mul_f32 v[104:105], v[104:105], v[118:119]
	v_pk_mul_f32 v[106:107], v[96:97], v[112:113]
	v_pk_mul_f32 v[96:97], v[100:101], v[110:111]
	v_pk_mul_f32 v[98:99], v[102:103], v[98:99]
	v_cvt_pk_bf16_f32 v96, v96, v97
	v_cvt_pk_bf16_f32 v97, v98, v99
	v_pk_mul_f32 v[98:99], v[104:105], v[108:109]
	v_pk_mul_f32 v[100:101], v[106:107], v[114:115]
	v_cvt_pk_bf16_f32 v98, v98, v99
	v_cvt_pk_bf16_f32 v99, v100, v101
	v_or_b32_e32 v95, 20, v6
	global_store_dwordx4 v[92:93], v[96:99], off offset:1024
	v_or_b32_e32 v92, v202, v95
	v_mov_b32_e32 v93, v203
	global_load_dwordx4 v[100:103], v7, s[72:73]
	global_load_dwordx4 v[104:107], v7, s[72:73] offset:16
	v_lshl_add_u32 v95, v95, 8, v9
	ds_read_b128 v[108:111], v95
	v_lshlrev_b64 v[92:93], 11, v[92:93]
	v_lshl_add_u64 v[92:93], s[6:7], 0, v[92:93]
	v_lshl_add_u64 v[92:93], v[92:93], 0, v[218:219]
	v_lshl_add_u64 v[92:93], v[92:93], 0, v[4:5]
	s_waitcnt lgkmcnt(0)
	v_lshlrev_b32_e32 v124, 16, v108
	v_and_b32_e32 v125, 0xffff0000, v108
	v_lshlrev_b32_e32 v120, 16, v109
	v_and_b32_e32 v121, 0xffff0000, v109
	v_pk_mul_f32 v[108:109], v[124:125], v[124:125]
	v_pk_mul_f32 v[122:123], v[120:121], v[120:121]
	v_add_f32_e32 v95, v108, v109
	v_lshlrev_b32_e32 v118, 16, v110
	v_and_b32_e32 v119, 0xffff0000, v110
	v_add_f32_e32 v95, v122, v95
	v_lshlrev_b32_e32 v112, 16, v111
	v_and_b32_e32 v113, 0xffff0000, v111
	v_pk_mul_f32 v[110:111], v[118:119], v[118:119]
	v_add_f32_e32 v95, v123, v95
	v_add_f32_e32 v95, v110, v95
	v_pk_mul_f32 v[116:117], v[112:113], v[112:113]
	v_add_f32_e32 v95, v111, v95
	v_add_f32_e32 v95, v116, v95
	v_add_f32_e32 v95, v117, v95
	s_waitcnt vmcnt(2)
; #define LAS __attribute__((address_space(3)))
; __device__ __forceinline__ unsigned pk2(float lo, float hi) { f32x2_t v = {lo, hi}; bf16x2_t b = __builtin_convertvector(v, bf16x2_t); return __builtin_bit_cast(unsigned, b); }
; template <bool NOMAX>
; __device__ __forceinline__ void diff_unit(const AttnCtx& C, int u, LAS unsigned char* lds) {
;     ...
;         for (int ps = 0; ps < 8; ++ps) {
;             const int rl = ps * 4 + (lanef >> 4); const size_t row = rowb + rl;
;             const v4u sv = *(const LAS v4u*)(stg + rl * 128 + cl * 8);
;             float xv[8];
;             xv[0] = __builtin_bit_cast(float, sv.x << 16); xv[1] = __builtin_bit_cast(float, sv.x & 0xffff0000u); xv[2] = __builtin_bit_cast(float, sv.y << 16); xv[3] = __builtin_bit_cast(float, sv.y & 0xffff0000u);
;             xv[4] = __builtin_bit_cast(float, sv.z << 16); xv[5] = __builtin_bit_cast(float, sv.z & 0xffff0000u); xv[6] = __builtin_bit_cast(float, sv.w << 16); xv[7] = __builtin_bit_cast(float, sv.w & 0xffff0000u);
;             const v4u gv = *(const v4u*)(C.GD + row * 512 + h * 128 + cl * 8);
;             float gg[8];
;             gg[0] = __builtin_bit_cast(float, gv.x << 16); gg[1] = __builtin_bit_cast(float, gv.x & 0xffff0000u); gg[2] = __builtin_bit_cast(float, gv.y << 16); gg[3] = __builtin_bit_cast(float, gv.y & 0xffff0000u);
;             gg[4] = __builtin_bit_cast(float, gv.z << 16); gg[5] = __builtin_bit_cast(float, gv.z & 0xffff0000u); gg[6] = __builtin_bit_cast(float, gv.w << 16); gg[7] = __builtin_bit_cast(float, gv.w & 0xffff0000u);
;             float sq = 0.f;
; #pragma unroll
;             for (int e = 0; e < 8; ++e) sq += xv[e] * xv[e];
;     ...
;             SQDPP(0xB1); SQDPP(0x4E); SQDPP(0x141); SQDPP(0x140);
;     ...
;             const float rs = (1.0f / sqrtf(sq * (1.0f / 128.0f) + EPSN)) * 0.8f;
;             const f32x4 s0 = *(const f32x4*)(C.subln + cl * 8), s1 = *(const f32x4*)(C.subln + cl * 8 + 4);
; #pragma unroll
;             for (int e = 0; e < 4; ++e) { xv[e] *= rs * s0[e]; xv[4 + e] *= rs * s1[e]; }
;             v4u ov; ov.x = pk2(xv[0] * gg[0], xv[1] * gg[1]); ov.y = pk2(xv[2] * gg[2], xv[3] * gg[3]); ov.z = pk2(xv[4] * gg[4], xv[5] * gg[5]); ov.w = pk2(xv[6] * gg[6], xv[7] * gg[7]);
;             *(v4u*)(C.MIX + row * 1024 + 512 + h * 128 + cl * 8) = ov;
	v_lshlrev_b32_e32 v114, 16, v147
	v_add_f32_dpp v95, v95, v95 quad_perm:[1,0,3,2] row_mask:0xf bank_mask:0xf bound_ctrl:1
	v_and_b32_e32 v115, 0xffff0000, v147
	v_lshlrev_b32_e32 v108, 16, v146
	v_add_f32_dpp v95, v95, v95 quad_perm:[2,3,0,1] row_mask:0xf bank_mask:0xf bound_ctrl:1
	v_and_b32_e32 v109, 0xffff0000, v146
	v_lshlrev_b32_e32 v98, 16, v145
	v_add_f32_dpp v95, v95, v95 row_half_mirror row_mask:0xf bank_mask:0xf bound_ctrl:1
	s_nop 1
	v_add_f32_dpp v95, v95, v95 row_mirror row_mask:0xf bank_mask:0xf bound_ctrl:1
	v_fmamk_f32 v95, v95, 0x3c000000, v217
	v_mul_f32_e32 v99, 0x4f800000, v95
	v_cmp_gt_f32_e32 vcc, s56, v95
	s_nop 1
	v_cndmask_b32_e32 v95, v95, v99, vcc
	v_sqrt_f32_e32 v99, v95
	s_nop 0
	v_add_u32_e32 v110, -1, v99
	v_fma_f32 v111, -v110, v99, v95
	v_cmp_ge_f32_e64 s[4:5], 0, v111
	v_add_u32_e32 v111, 1, v99
	s_nop 0
	v_cndmask_b32_e64 v110, v99, v110, s[4:5]
	v_fma_f32 v99, -v111, v99, v95
	v_cmp_lt_f32_e64 s[4:5], 0, v99
	s_nop 1
	v_cndmask_b32_e64 v99, v110, v111, s[4:5]
	v_mul_f32_e32 v110, 0x37800000, v99
	v_cndmask_b32_e32 v99, v99, v110, vcc
	v_cmp_class_f32_e32 vcc, v95, v228
	v_lshlrev_b32_e32 v110, 16, v144
	v_and_b32_e32 v111, 0xffff0000, v144
	v_cndmask_b32_e32 v95, v99, v95, vcc
	v_div_scale_f32 v116, s[0:1], v95, v95, 1.0
	v_rcp_f32_e32 v117, v116
	v_and_b32_e32 v99, 0xffff0000, v145
	v_fma_f32 v96, -v116, v117, 1.0
	v_fmac_f32_e32 v117, v96, v117
	v_div_scale_f32 v96, vcc, 1.0, v95, 1.0
	v_mul_f32_e32 v97, v96, v117
	v_fma_f32 v122, -v116, v97, v96
	v_fmac_f32_e32 v97, v122, v117
	v_fma_f32 v96, -v116, v97, v96
	v_div_fmas_f32 v96, v96, v117, v97
	v_div_fixup_f32 v95, v96, v95, 1.0
	v_mul_f32_e32 v96, 0x3f4ccccd, v95
	s_waitcnt vmcnt(1)
	v_pk_mul_f32 v[100:101], v[100:101], v[96:97] op_sel_hi:[1,0]
	v_pk_mul_f32 v[102:103], v[102:103], v[96:97] op_sel_hi:[1,0]
	v_pk_mul_f32 v[100:101], v[100:101], v[124:125]
	s_waitcnt vmcnt(0)
	v_pk_mul_f32 v[104:105], v[104:105], v[96:97] op_sel_hi:[1,0]
	v_pk_mul_f32 v[102:103], v[102:103], v[120:121]
	v_pk_mul_f32 v[96:97], v[106:107], v[96:97] op_sel_hi:[1,0]
	v_pk_mul_f32 v[104:105], v[104:105], v[118:119]
	v_pk_mul_f32 v[106:107], v[96:97], v[112:113]
	v_pk_mul_f32 v[96:97], v[100:101], v[110:111]
	v_pk_mul_f32 v[98:99], v[102:103], v[98:99]
	v_cvt_pk_bf16_f32 v96, v96, v97
	v_cvt_pk_bf16_f32 v97, v98, v99
	v_pk_mul_f32 v[98:99], v[104:105], v[108:109]
	v_pk_mul_f32 v[100:101], v[106:107], v[114:115]
	v_cvt_pk_bf16_f32 v98, v98, v99
	v_cvt_pk_bf16_f32 v99, v100, v101
	v_or_b32_e32 v95, 24, v6
	global_store_dwordx4 v[92:93], v[96:99], off offset:1024
	v_or_b32_e32 v92, v202, v95
	v_mov_b32_e32 v93, v203
	global_load_dwordx4 v[100:103], v7, s[72:73]
	global_load_dwordx4 v[104:107], v7, s[72:73] offset:16
	v_lshl_add_u32 v95, v95, 8, v9
	ds_read_b128 v[108:111], v95
	v_lshlrev_b64 v[92:93], 11, v[92:93]
	v_lshl_add_u64 v[92:93], s[6:7], 0, v[92:93]
	v_lshl_add_u64 v[92:93], v[92:93], 0, v[218:219]
	v_or_b32_e32 v6, 28, v6
	s_waitcnt lgkmcnt(0)
	v_lshlrev_b32_e32 v124, 16, v108
	v_and_b32_e32 v125, 0xffff0000, v108
	v_lshlrev_b32_e32 v120, 16, v109
	v_and_b32_e32 v121, 0xffff0000, v109
	v_pk_mul_f32 v[108:109], v[124:125], v[124:125]
	v_pk_mul_f32 v[122:123], v[120:121], v[120:121]
	v_add_f32_e32 v95, v108, v109
	v_lshlrev_b32_e32 v118, 16, v110
	v_and_b32_e32 v119, 0xffff0000, v110
	v_add_f32_e32 v95, v122, v95
	v_lshlrev_b32_e32 v112, 16, v111
	v_and_b32_e32 v113, 0xffff0000, v111
	v_pk_mul_f32 v[110:111], v[118:119], v[118:119]
	v_add_f32_e32 v95, v123, v95
	v_add_f32_e32 v95, v110, v95
	v_pk_mul_f32 v[116:117], v[112:113], v[112:113]
	v_add_f32_e32 v95, v111, v95
	v_add_f32_e32 v95, v116, v95
	v_add_f32_e32 v95, v117, v95
	v_lshl_add_u64 v[92:93], v[92:93], 0, v[4:5]
	v_or_b32_e32 v202, v202, v6
	v_add_f32_dpp v95, v95, v95 quad_perm:[1,0,3,2] row_mask:0xf bank_mask:0xf bound_ctrl:1
	v_lshl_add_u32 v6, v6, 8, v9
	s_waitcnt vmcnt(2)
	v_lshlrev_b32_e32 v114, 16, v151
	v_add_f32_dpp v95, v95, v95 quad_perm:[2,3,0,1] row_mask:0xf bank_mask:0xf bound_ctrl:1
	v_and_b32_e32 v115, 0xffff0000, v151
	v_lshlrev_b32_e32 v108, 16, v150
	v_add_f32_dpp v95, v95, v95 row_half_mirror row_mask:0xf bank_mask:0xf bound_ctrl:1
	v_and_b32_e32 v109, 0xffff0000, v150
	v_lshlrev_b32_e32 v98, 16, v149
	v_add_f32_dpp v95, v95, v95 row_mirror row_mask:0xf bank_mask:0xf bound_ctrl:1
	v_fmamk_f32 v95, v95, 0x3c000000, v217
	v_mul_f32_e32 v99, 0x4f800000, v95
	v_cmp_gt_f32_e32 vcc, s56, v95
	s_nop 1
	v_cndmask_b32_e32 v95, v95, v99, vcc
	v_sqrt_f32_e32 v99, v95
	s_nop 0
	v_add_u32_e32 v110, -1, v99
	v_fma_f32 v111, -v110, v99, v95
	v_cmp_ge_f32_e64 s[4:5], 0, v111
	v_add_u32_e32 v111, 1, v99
	s_nop 0
	v_cndmask_b32_e64 v110, v99, v110, s[4:5]
	v_fma_f32 v99, -v111, v99, v95
	v_cmp_lt_f32_e64 s[4:5], 0, v99
	s_nop 1
	v_cndmask_b32_e64 v99, v110, v111, s[4:5]
	v_mul_f32_e32 v110, 0x37800000, v99
	v_cndmask_b32_e32 v99, v99, v110, vcc
	v_cmp_class_f32_e32 vcc, v95, v228
	v_lshlrev_b32_e32 v110, 16, v148
	v_and_b32_e32 v111, 0xffff0000, v148
	v_cndmask_b32_e32 v95, v99, v95, vcc
	v_div_scale_f32 v116, s[0:1], v95, v95, 1.0
	v_rcp_f32_e32 v117, v116
	v_and_b32_e32 v99, 0xffff0000, v149
	v_fma_f32 v96, -v116, v117, 1.0
	v_fmac_f32_e32 v117, v96, v117
	v_div_scale_f32 v96, vcc, 1.0, v95, 1.0
	v_mul_f32_e32 v97, v96, v117
	v_fma_f32 v122, -v116, v97, v96
	v_fmac_f32_e32 v97, v122, v117
	v_fma_f32 v96, -v116, v97, v96
	v_div_fmas_f32 v96, v96, v117, v97
	v_div_fixup_f32 v95, v96, v95, 1.0
	v_mul_f32_e32 v96, 0x3f4ccccd, v95
	s_waitcnt vmcnt(1)
; #define LAS __attribute__((address_space(3)))
; __device__ __forceinline__ unsigned pk2(float lo, float hi) { f32x2_t v = {lo, hi}; bf16x2_t b = __builtin_convertvector(v, bf16x2_t); return __builtin_bit_cast(unsigned, b); }
; template <bool NOMAX>
; __device__ __forceinline__ void diff_unit(const AttnCtx& C, int u, LAS unsigned char* lds) {
;     ...
;         for (int ps = 0; ps < 8; ++ps) {
;             const int rl = ps * 4 + (lanef >> 4); const size_t row = rowb + rl;
;             const v4u sv = *(const LAS v4u*)(stg + rl * 128 + cl * 8);
;             float xv[8];
;             xv[0] = __builtin_bit_cast(float, sv.x << 16); xv[1] = __builtin_bit_cast(float, sv.x & 0xffff0000u); xv[2] = __builtin_bit_cast(float, sv.y << 16); xv[3] = __builtin_bit_cast(float, sv.y & 0xffff0000u);
;             xv[4] = __builtin_bit_cast(float, sv.z << 16); xv[5] = __builtin_bit_cast(float, sv.z & 0xffff0000u); xv[6] = __builtin_bit_cast(float, sv.w << 16); xv[7] = __builtin_bit_cast(float, sv.w & 0xffff0000u);
;             const v4u gv = *(const v4u*)(C.GD + row * 512 + h * 128 + cl * 8);
;             float gg[8];
;             gg[0] = __builtin_bit_cast(float, gv.x << 16); gg[1] = __builtin_bit_cast(float, gv.x & 0xffff0000u); gg[2] = __builtin_bit_cast(float, gv.y << 16); gg[3] = __builtin_bit_cast(float, gv.y & 0xffff0000u);
;             gg[4] = __builtin_bit_cast(float, gv.z << 16); gg[5] = __builtin_bit_cast(float, gv.z & 0xffff0000u); gg[6] = __builtin_bit_cast(float, gv.w << 16); gg[7] = __builtin_bit_cast(float, gv.w & 0xffff0000u);
;             float sq = 0.f;
; #pragma unroll
;             for (int e = 0; e < 8; ++e) sq += xv[e] * xv[e];
;     ...
;             SQDPP(0xB1); SQDPP(0x4E); SQDPP(0x141); SQDPP(0x140);
;     ...
;             const float rs = (1.0f / sqrtf(sq * (1.0f / 128.0f) + EPSN)) * 0.8f;
;             const f32x4 s0 = *(const f32x4*)(C.subln + cl * 8), s1 = *(const f32x4*)(C.subln + cl * 8 + 4);
; #pragma unroll
;             for (int e = 0; e < 4; ++e) { xv[e] *= rs * s0[e]; xv[4 + e] *= rs * s1[e]; }
;             v4u ov; ov.x = pk2(xv[0] * gg[0], xv[1] * gg[1]); ov.y = pk2(xv[2] * gg[2], xv[3] * gg[3]); ov.z = pk2(xv[4] * gg[4], xv[5] * gg[5]); ov.w = pk2(xv[6] * gg[6], xv[7] * gg[7]);
;             *(v4u*)(C.MIX + row * 1024 + 512 + h * 128 + cl * 8) = ov;
	v_pk_mul_f32 v[100:101], v[100:101], v[96:97] op_sel_hi:[1,0]
	v_pk_mul_f32 v[102:103], v[102:103], v[96:97] op_sel_hi:[1,0]
	v_pk_mul_f32 v[100:101], v[100:101], v[124:125]
	s_waitcnt vmcnt(0)
	v_pk_mul_f32 v[104:105], v[104:105], v[96:97] op_sel_hi:[1,0]
	v_pk_mul_f32 v[102:103], v[102:103], v[120:121]
	v_pk_mul_f32 v[96:97], v[106:107], v[96:97] op_sel_hi:[1,0]
	v_pk_mul_f32 v[104:105], v[104:105], v[118:119]
	v_pk_mul_f32 v[106:107], v[96:97], v[112:113]
	v_pk_mul_f32 v[96:97], v[100:101], v[110:111]
	v_pk_mul_f32 v[98:99], v[102:103], v[98:99]
	v_cvt_pk_bf16_f32 v96, v96, v97
	v_cvt_pk_bf16_f32 v97, v98, v99
	v_pk_mul_f32 v[98:99], v[104:105], v[108:109]
	v_pk_mul_f32 v[100:101], v[106:107], v[114:115]
	v_cvt_pk_bf16_f32 v98, v98, v99
	v_cvt_pk_bf16_f32 v99, v100, v101
	global_store_dwordx4 v[92:93], v[96:99], off offset:1024
	global_load_dwordx4 v[100:103], v7, s[72:73]
	global_load_dwordx4 v[104:107], v7, s[72:73] offset:16
	ds_read_b128 v[108:111], v6
	s_waitcnt lgkmcnt(0)
	v_lshlrev_b32_e32 v120, 16, v108
	v_and_b32_e32 v121, 0xffff0000, v108
	v_lshlrev_b32_e32 v116, 16, v109
	v_and_b32_e32 v117, 0xffff0000, v109
	v_pk_mul_f32 v[108:109], v[120:121], v[120:121]
	v_pk_mul_f32 v[118:119], v[116:117], v[116:117]
	v_add_f32_e32 v9, v108, v109
	v_lshlrev_b32_e32 v114, 16, v110
	v_and_b32_e32 v115, 0xffff0000, v110
	v_add_f32_e32 v9, v118, v9
	v_lshlrev_b32_e32 v6, 16, v111
	v_and_b32_e32 v7, 0xffff0000, v111
	v_pk_mul_f32 v[110:111], v[114:115], v[114:115]
	v_add_f32_e32 v9, v119, v9
	v_add_f32_e32 v9, v110, v9
	v_pk_mul_f32 v[112:113], v[6:7], v[6:7]
	v_add_f32_e32 v9, v111, v9
	v_add_f32_e32 v9, v112, v9
	v_add_f32_e32 v9, v113, v9
	s_waitcnt vmcnt(2)
	v_lshlrev_b32_e32 v92, 16, v155
	v_add_f32_dpp v9, v9, v9 quad_perm:[1,0,3,2] row_mask:0xf bank_mask:0xf bound_ctrl:1
	v_and_b32_e32 v93, 0xffff0000, v155
	v_and_b32_e32 v111, 0xffff0000, v152
	v_add_f32_dpp v9, v9, v9 quad_perm:[2,3,0,1] row_mask:0xf bank_mask:0xf bound_ctrl:1
	v_lshlrev_b32_e32 v108, 16, v154
	v_and_b32_e32 v109, 0xffff0000, v154
	v_add_f32_dpp v9, v9, v9 row_half_mirror row_mask:0xf bank_mask:0xf bound_ctrl:1
	v_lshlrev_b32_e32 v98, 16, v153
	s_nop 0
	v_add_f32_dpp v9, v9, v9 row_mirror row_mask:0xf bank_mask:0xf bound_ctrl:1
	v_fmamk_f32 v9, v9, 0x3c000000, v217
	v_mul_f32_e32 v95, 0x4f800000, v9
	v_cmp_gt_f32_e32 vcc, s56, v9
	s_nop 1
	v_cndmask_b32_e32 v9, v9, v95, vcc
	v_sqrt_f32_e32 v95, v9
	s_nop 0
	v_add_u32_e32 v99, -1, v95
	v_fma_f32 v110, -v99, v95, v9
	v_cmp_ge_f32_e64 s[4:5], 0, v110
	v_add_u32_e32 v110, 1, v95
	s_nop 0
	v_cndmask_b32_e64 v99, v95, v99, s[4:5]
	v_fma_f32 v95, -v110, v95, v9
	v_cmp_lt_f32_e64 s[4:5], 0, v95
	s_nop 1
	v_cndmask_b32_e64 v95, v99, v110, s[4:5]
	v_mul_f32_e32 v99, 0x37800000, v95
	v_cndmask_b32_e32 v95, v95, v99, vcc
	v_cmp_class_f32_e32 vcc, v9, v228
	v_lshlrev_b32_e32 v110, 16, v152
	v_and_b32_e32 v99, 0xffff0000, v153
	v_cndmask_b32_e32 v9, v95, v9, vcc
	v_div_scale_f32 v95, s[0:1], v9, v9, 1.0
	v_rcp_f32_e32 v112, v95
	s_nop 0
	v_fma_f32 v96, -v95, v112, 1.0
	v_fmac_f32_e32 v112, v96, v112
	v_div_scale_f32 v96, vcc, 1.0, v9, 1.0
	v_mul_f32_e32 v97, v96, v112
	v_fma_f32 v113, -v95, v97, v96
	v_fmac_f32_e32 v97, v113, v112
	v_fma_f32 v95, -v95, v97, v96
	v_div_fmas_f32 v95, v95, v112, v97
	v_div_fixup_f32 v9, v95, v9, 1.0
	v_mul_f32_e32 v96, 0x3f4ccccd, v9
	s_waitcnt vmcnt(1)
	v_pk_mul_f32 v[100:101], v[100:101], v[96:97] op_sel_hi:[1,0]
	v_pk_mul_f32 v[102:103], v[102:103], v[96:97] op_sel_hi:[1,0]
	v_pk_mul_f32 v[100:101], v[100:101], v[120:121]
	s_waitcnt vmcnt(0)
	v_pk_mul_f32 v[104:105], v[104:105], v[96:97] op_sel_hi:[1,0]
	v_pk_mul_f32 v[102:103], v[102:103], v[116:117]
	v_pk_mul_f32 v[96:97], v[106:107], v[96:97] op_sel_hi:[1,0]
	v_pk_mul_f32 v[104:105], v[104:105], v[114:115]
	v_pk_mul_f32 v[6:7], v[96:97], v[6:7]
	v_pk_mul_f32 v[96:97], v[100:101], v[110:111]
	v_pk_mul_f32 v[98:99], v[102:103], v[98:99]
	v_cvt_pk_bf16_f32 v96, v96, v97
	v_cvt_pk_bf16_f32 v97, v98, v99
	v_pk_mul_f32 v[98:99], v[104:105], v[108:109]
	v_pk_mul_f32 v[6:7], v[6:7], v[92:93]
	v_cvt_pk_bf16_f32 v98, v98, v99
	v_cvt_pk_bf16_f32 v99, v6, v7
	v_lshlrev_b64 v[6:7], 11, v[202:203]
	v_lshl_add_u64 v[6:7], s[6:7], 0, v[6:7]
	v_lshl_add_u64 v[6:7], v[6:7], 0, v[218:219]
	v_lshl_add_u64 v[4:5], v[6:7], 0, v[4:5]
	s_mov_b64 s[6:7], 0
	global_store_dwordx4 v[4:5], v[96:99], off offset:1024
